# K block means: 32 row requests in flight per item instead of 8 dependent trips of 4
# speedup vs baseline: 1.0025x; 1.0025x over previous
.LBB0_1221:
	v_add_co_u32_e32 v156, vcc, 0xfffe2000, v16
	s_nop 0
	v_addc_co_u32_e32 v157, vcc, -1, v17, vcc
	global_load_dwordx4 v[28:31], v[156:157], off
	v_add_co_u32_e32 v156, vcc, 0xa000, v156
	s_nop 0
	v_addc_co_u32_e32 v157, vcc, 0, v157, vcc
	global_load_dwordx4 v[32:35], v[156:157], off
	v_add_co_u32_e32 v156, vcc, 0xa000, v156
	s_nop 0
	v_addc_co_u32_e32 v157, vcc, 0, v157, vcc
	global_load_dwordx4 v[36:39], v[156:157], off
	v_add_co_u32_e32 v156, vcc, 0xa000, v156
	s_nop 0
	v_addc_co_u32_e32 v157, vcc, 0, v157, vcc
	global_load_dwordx4 v[40:43], v[156:157], off
	v_add_co_u32_e32 v156, vcc, 0xa000, v156
	s_nop 0
	v_addc_co_u32_e32 v157, vcc, 0, v157, vcc
	global_load_dwordx4 v[44:47], v[156:157], off
	v_add_co_u32_e32 v156, vcc, 0xa000, v156
	s_nop 0
	v_addc_co_u32_e32 v157, vcc, 0, v157, vcc
	global_load_dwordx4 v[48:51], v[156:157], off
	v_add_co_u32_e32 v156, vcc, 0xa000, v156
	s_nop 0
	v_addc_co_u32_e32 v157, vcc, 0, v157, vcc
	global_load_dwordx4 v[52:55], v[156:157], off
	v_add_co_u32_e32 v156, vcc, 0xa000, v156
	s_nop 0
	v_addc_co_u32_e32 v157, vcc, 0, v157, vcc
	global_load_dwordx4 v[56:59], v[156:157], off
	v_add_co_u32_e32 v156, vcc, 0xa000, v156
	s_nop 0
	v_addc_co_u32_e32 v157, vcc, 0, v157, vcc
	global_load_dwordx4 v[60:63], v[156:157], off
	v_add_co_u32_e32 v156, vcc, 0xa000, v156
	s_nop 0
	v_addc_co_u32_e32 v157, vcc, 0, v157, vcc
	global_load_dwordx4 v[64:67], v[156:157], off
	v_add_co_u32_e32 v156, vcc, 0xa000, v156
	s_nop 0
	v_addc_co_u32_e32 v157, vcc, 0, v157, vcc
	global_load_dwordx4 v[68:71], v[156:157], off
	v_add_co_u32_e32 v156, vcc, 0xa000, v156
	s_nop 0
	v_addc_co_u32_e32 v157, vcc, 0, v157, vcc
	global_load_dwordx4 v[72:75], v[156:157], off
	v_add_co_u32_e32 v156, vcc, 0xa000, v156
	s_nop 0
	v_addc_co_u32_e32 v157, vcc, 0, v157, vcc
	global_load_dwordx4 v[76:79], v[156:157], off
	v_add_co_u32_e32 v156, vcc, 0xa000, v156
	s_nop 0
	v_addc_co_u32_e32 v157, vcc, 0, v157, vcc
	global_load_dwordx4 v[80:83], v[156:157], off
	v_add_co_u32_e32 v156, vcc, 0xa000, v156
	s_nop 0
	v_addc_co_u32_e32 v157, vcc, 0, v157, vcc
	global_load_dwordx4 v[84:87], v[156:157], off
	v_add_co_u32_e32 v156, vcc, 0xa000, v156
	s_nop 0
	v_addc_co_u32_e32 v157, vcc, 0, v157, vcc
	global_load_dwordx4 v[88:91], v[156:157], off
	v_add_co_u32_e32 v156, vcc, 0xa000, v156
	s_nop 0
	v_addc_co_u32_e32 v157, vcc, 0, v157, vcc
	global_load_dwordx4 v[92:95], v[156:157], off
	v_add_co_u32_e32 v156, vcc, 0xa000, v156
	s_nop 0
	v_addc_co_u32_e32 v157, vcc, 0, v157, vcc
	global_load_dwordx4 v[96:99], v[156:157], off
	v_add_co_u32_e32 v156, vcc, 0xa000, v156
	s_nop 0
	v_addc_co_u32_e32 v157, vcc, 0, v157, vcc
	global_load_dwordx4 v[100:103], v[156:157], off
	v_add_co_u32_e32 v156, vcc, 0xa000, v156
	s_nop 0
	v_addc_co_u32_e32 v157, vcc, 0, v157, vcc
	global_load_dwordx4 v[104:107], v[156:157], off
	v_add_co_u32_e32 v156, vcc, 0xa000, v156
	s_nop 0
	v_addc_co_u32_e32 v157, vcc, 0, v157, vcc
	global_load_dwordx4 v[108:111], v[156:157], off
	v_add_co_u32_e32 v156, vcc, 0xa000, v156
	s_nop 0
	v_addc_co_u32_e32 v157, vcc, 0, v157, vcc
	global_load_dwordx4 v[112:115], v[156:157], off
	v_add_co_u32_e32 v156, vcc, 0xa000, v156
	s_nop 0
	v_addc_co_u32_e32 v157, vcc, 0, v157, vcc
	global_load_dwordx4 v[116:119], v[156:157], off
	v_add_co_u32_e32 v156, vcc, 0xa000, v156
	s_nop 0
	v_addc_co_u32_e32 v157, vcc, 0, v157, vcc
	global_load_dwordx4 v[120:123], v[156:157], off
	v_add_co_u32_e32 v156, vcc, 0xa000, v156
	s_nop 0
	v_addc_co_u32_e32 v157, vcc, 0, v157, vcc
	global_load_dwordx4 v[124:127], v[156:157], off
	v_add_co_u32_e32 v156, vcc, 0xa000, v156
	s_nop 0
	v_addc_co_u32_e32 v157, vcc, 0, v157, vcc
	global_load_dwordx4 v[128:131], v[156:157], off
	v_add_co_u32_e32 v156, vcc, 0xa000, v156
	s_nop 0
	v_addc_co_u32_e32 v157, vcc, 0, v157, vcc
	global_load_dwordx4 v[132:135], v[156:157], off
	v_add_co_u32_e32 v156, vcc, 0xa000, v156
	s_nop 0
	v_addc_co_u32_e32 v157, vcc, 0, v157, vcc
	global_load_dwordx4 v[136:139], v[156:157], off
	v_add_co_u32_e32 v156, vcc, 0xa000, v156
	s_nop 0
	v_addc_co_u32_e32 v157, vcc, 0, v157, vcc
	global_load_dwordx4 v[140:143], v[156:157], off
	v_add_co_u32_e32 v156, vcc, 0xa000, v156
	s_nop 0
	v_addc_co_u32_e32 v157, vcc, 0, v157, vcc
	global_load_dwordx4 v[144:147], v[156:157], off
	v_add_co_u32_e32 v156, vcc, 0xa000, v156
	s_nop 0
	v_addc_co_u32_e32 v157, vcc, 0, v157, vcc
	global_load_dwordx4 v[148:151], v[156:157], off
	v_add_co_u32_e32 v156, vcc, 0xa000, v156
	s_nop 0
	v_addc_co_u32_e32 v157, vcc, 0, v157, vcc
	global_load_dwordx4 v[152:155], v[156:157], off
	s_waitcnt vmcnt(31)
	v_lshlrev_b32_e32 v158, 16, v28
	v_and_b32_e32 v28, 0xffff0000, v28
	v_add_f32_e32 v14, v14, v158
	v_add_f32_e32 v15, v15, v28
	v_lshlrev_b32_e32 v158, 16, v29
	v_and_b32_e32 v29, 0xffff0000, v29
	v_add_f32_e32 v12, v12, v158
	v_add_f32_e32 v13, v13, v29
	v_lshlrev_b32_e32 v158, 16, v30
	v_and_b32_e32 v30, 0xffff0000, v30
	v_add_f32_e32 v10, v10, v158
	v_add_f32_e32 v11, v11, v30
	v_lshlrev_b32_e32 v158, 16, v31
	v_and_b32_e32 v31, 0xffff0000, v31
	v_add_f32_e32 v8, v8, v158
	v_add_f32_e32 v9, v9, v31
	s_waitcnt vmcnt(30)
	v_lshlrev_b32_e32 v158, 16, v32
	v_and_b32_e32 v32, 0xffff0000, v32
	v_add_f32_e32 v14, v14, v158
	v_add_f32_e32 v15, v15, v32
	v_lshlrev_b32_e32 v158, 16, v33
	v_and_b32_e32 v33, 0xffff0000, v33
	v_add_f32_e32 v12, v12, v158
	v_add_f32_e32 v13, v13, v33
	v_lshlrev_b32_e32 v158, 16, v34
	v_and_b32_e32 v34, 0xffff0000, v34
	v_add_f32_e32 v10, v10, v158
	v_add_f32_e32 v11, v11, v34
	v_lshlrev_b32_e32 v158, 16, v35
	v_and_b32_e32 v35, 0xffff0000, v35
	v_add_f32_e32 v8, v8, v158
	v_add_f32_e32 v9, v9, v35
	s_waitcnt vmcnt(29)
	v_lshlrev_b32_e32 v158, 16, v36
	v_and_b32_e32 v36, 0xffff0000, v36
	v_add_f32_e32 v14, v14, v158
	v_add_f32_e32 v15, v15, v36
	v_lshlrev_b32_e32 v158, 16, v37
	v_and_b32_e32 v37, 0xffff0000, v37
	v_add_f32_e32 v12, v12, v158
	v_add_f32_e32 v13, v13, v37
	v_lshlrev_b32_e32 v158, 16, v38
	v_and_b32_e32 v38, 0xffff0000, v38
	v_add_f32_e32 v10, v10, v158
	v_add_f32_e32 v11, v11, v38
	v_lshlrev_b32_e32 v158, 16, v39
	v_and_b32_e32 v39, 0xffff0000, v39
	v_add_f32_e32 v8, v8, v158
	v_add_f32_e32 v9, v9, v39
	s_waitcnt vmcnt(28)
	v_lshlrev_b32_e32 v158, 16, v40
	v_and_b32_e32 v40, 0xffff0000, v40
	v_add_f32_e32 v14, v14, v158
	v_add_f32_e32 v15, v15, v40
	v_lshlrev_b32_e32 v158, 16, v41
	v_and_b32_e32 v41, 0xffff0000, v41
	v_add_f32_e32 v12, v12, v158
	v_add_f32_e32 v13, v13, v41
	v_lshlrev_b32_e32 v158, 16, v42
	v_and_b32_e32 v42, 0xffff0000, v42
	v_add_f32_e32 v10, v10, v158
	v_add_f32_e32 v11, v11, v42
	v_lshlrev_b32_e32 v158, 16, v43
	v_and_b32_e32 v43, 0xffff0000, v43
	v_add_f32_e32 v8, v8, v158
	v_add_f32_e32 v9, v9, v43
	s_waitcnt vmcnt(27)
	v_lshlrev_b32_e32 v158, 16, v44
	v_and_b32_e32 v44, 0xffff0000, v44
	v_add_f32_e32 v14, v14, v158
	v_add_f32_e32 v15, v15, v44
	v_lshlrev_b32_e32 v158, 16, v45
	v_and_b32_e32 v45, 0xffff0000, v45
	v_add_f32_e32 v12, v12, v158
	v_add_f32_e32 v13, v13, v45
	v_lshlrev_b32_e32 v158, 16, v46
	v_and_b32_e32 v46, 0xffff0000, v46
	v_add_f32_e32 v10, v10, v158
	v_add_f32_e32 v11, v11, v46
	v_lshlrev_b32_e32 v158, 16, v47
	v_and_b32_e32 v47, 0xffff0000, v47
	v_add_f32_e32 v8, v8, v158
	v_add_f32_e32 v9, v9, v47
	s_waitcnt vmcnt(26)
	v_lshlrev_b32_e32 v158, 16, v48
	v_and_b32_e32 v48, 0xffff0000, v48
	v_add_f32_e32 v14, v14, v158
	v_add_f32_e32 v15, v15, v48
	v_lshlrev_b32_e32 v158, 16, v49
	v_and_b32_e32 v49, 0xffff0000, v49
	v_add_f32_e32 v12, v12, v158
	v_add_f32_e32 v13, v13, v49
	v_lshlrev_b32_e32 v158, 16, v50
	v_and_b32_e32 v50, 0xffff0000, v50
	v_add_f32_e32 v10, v10, v158
	v_add_f32_e32 v11, v11, v50
	v_lshlrev_b32_e32 v158, 16, v51
	v_and_b32_e32 v51, 0xffff0000, v51
	v_add_f32_e32 v8, v8, v158
	v_add_f32_e32 v9, v9, v51
	s_waitcnt vmcnt(25)
	v_lshlrev_b32_e32 v158, 16, v52
	v_and_b32_e32 v52, 0xffff0000, v52
	v_add_f32_e32 v14, v14, v158
	v_add_f32_e32 v15, v15, v52
	v_lshlrev_b32_e32 v158, 16, v53
	v_and_b32_e32 v53, 0xffff0000, v53
	v_add_f32_e32 v12, v12, v158
	v_add_f32_e32 v13, v13, v53
	v_lshlrev_b32_e32 v158, 16, v54
	v_and_b32_e32 v54, 0xffff0000, v54
	v_add_f32_e32 v10, v10, v158
	v_add_f32_e32 v11, v11, v54
	v_lshlrev_b32_e32 v158, 16, v55
	v_and_b32_e32 v55, 0xffff0000, v55
	v_add_f32_e32 v8, v8, v158
	v_add_f32_e32 v9, v9, v55
	s_waitcnt vmcnt(24)
	v_lshlrev_b32_e32 v158, 16, v56
	v_and_b32_e32 v56, 0xffff0000, v56
	v_add_f32_e32 v14, v14, v158
	v_add_f32_e32 v15, v15, v56
	v_lshlrev_b32_e32 v158, 16, v57
	v_and_b32_e32 v57, 0xffff0000, v57
	v_add_f32_e32 v12, v12, v158
	v_add_f32_e32 v13, v13, v57
	v_lshlrev_b32_e32 v158, 16, v58
	v_and_b32_e32 v58, 0xffff0000, v58
	v_add_f32_e32 v10, v10, v158
	v_add_f32_e32 v11, v11, v58
	v_lshlrev_b32_e32 v158, 16, v59
	v_and_b32_e32 v59, 0xffff0000, v59
	v_add_f32_e32 v8, v8, v158
	v_add_f32_e32 v9, v9, v59
	s_waitcnt vmcnt(23)
	v_lshlrev_b32_e32 v158, 16, v60
	v_and_b32_e32 v60, 0xffff0000, v60
	v_add_f32_e32 v14, v14, v158
	v_add_f32_e32 v15, v15, v60
	v_lshlrev_b32_e32 v158, 16, v61
	v_and_b32_e32 v61, 0xffff0000, v61
	v_add_f32_e32 v12, v12, v158
	v_add_f32_e32 v13, v13, v61
	v_lshlrev_b32_e32 v158, 16, v62
	v_and_b32_e32 v62, 0xffff0000, v62
	v_add_f32_e32 v10, v10, v158
	v_add_f32_e32 v11, v11, v62
	v_lshlrev_b32_e32 v158, 16, v63
	v_and_b32_e32 v63, 0xffff0000, v63
	v_add_f32_e32 v8, v8, v158
	v_add_f32_e32 v9, v9, v63
	s_waitcnt vmcnt(22)
	v_lshlrev_b32_e32 v158, 16, v64
	v_and_b32_e32 v64, 0xffff0000, v64
	v_add_f32_e32 v14, v14, v158
	v_add_f32_e32 v15, v15, v64
	v_lshlrev_b32_e32 v158, 16, v65
	v_and_b32_e32 v65, 0xffff0000, v65
	v_add_f32_e32 v12, v12, v158
	v_add_f32_e32 v13, v13, v65
	v_lshlrev_b32_e32 v158, 16, v66
	v_and_b32_e32 v66, 0xffff0000, v66
	v_add_f32_e32 v10, v10, v158
	v_add_f32_e32 v11, v11, v66
	v_lshlrev_b32_e32 v158, 16, v67
	v_and_b32_e32 v67, 0xffff0000, v67
	v_add_f32_e32 v8, v8, v158
	v_add_f32_e32 v9, v9, v67
	s_waitcnt vmcnt(21)
	v_lshlrev_b32_e32 v158, 16, v68
	v_and_b32_e32 v68, 0xffff0000, v68
	v_add_f32_e32 v14, v14, v158
	v_add_f32_e32 v15, v15, v68
	v_lshlrev_b32_e32 v158, 16, v69
	v_and_b32_e32 v69, 0xffff0000, v69
	v_add_f32_e32 v12, v12, v158
	v_add_f32_e32 v13, v13, v69
	v_lshlrev_b32_e32 v158, 16, v70
	v_and_b32_e32 v70, 0xffff0000, v70
	v_add_f32_e32 v10, v10, v158
	v_add_f32_e32 v11, v11, v70
	v_lshlrev_b32_e32 v158, 16, v71
	v_and_b32_e32 v71, 0xffff0000, v71
	v_add_f32_e32 v8, v8, v158
	v_add_f32_e32 v9, v9, v71
	s_waitcnt vmcnt(20)
	v_lshlrev_b32_e32 v158, 16, v72
	v_and_b32_e32 v72, 0xffff0000, v72
	v_add_f32_e32 v14, v14, v158
	v_add_f32_e32 v15, v15, v72
	v_lshlrev_b32_e32 v158, 16, v73
	v_and_b32_e32 v73, 0xffff0000, v73
	v_add_f32_e32 v12, v12, v158
	v_add_f32_e32 v13, v13, v73
	v_lshlrev_b32_e32 v158, 16, v74
	v_and_b32_e32 v74, 0xffff0000, v74
	v_add_f32_e32 v10, v10, v158
	v_add_f32_e32 v11, v11, v74
	v_lshlrev_b32_e32 v158, 16, v75
	v_and_b32_e32 v75, 0xffff0000, v75
	v_add_f32_e32 v8, v8, v158
	v_add_f32_e32 v9, v9, v75
	s_waitcnt vmcnt(19)
	v_lshlrev_b32_e32 v158, 16, v76
	v_and_b32_e32 v76, 0xffff0000, v76
	v_add_f32_e32 v14, v14, v158
	v_add_f32_e32 v15, v15, v76
	v_lshlrev_b32_e32 v158, 16, v77
	v_and_b32_e32 v77, 0xffff0000, v77
	v_add_f32_e32 v12, v12, v158
	v_add_f32_e32 v13, v13, v77
	v_lshlrev_b32_e32 v158, 16, v78
	v_and_b32_e32 v78, 0xffff0000, v78
	v_add_f32_e32 v10, v10, v158
	v_add_f32_e32 v11, v11, v78
	v_lshlrev_b32_e32 v158, 16, v79
	v_and_b32_e32 v79, 0xffff0000, v79
	v_add_f32_e32 v8, v8, v158
	v_add_f32_e32 v9, v9, v79
	s_waitcnt vmcnt(18)
	v_lshlrev_b32_e32 v158, 16, v80
	v_and_b32_e32 v80, 0xffff0000, v80
	v_add_f32_e32 v14, v14, v158
	v_add_f32_e32 v15, v15, v80
	v_lshlrev_b32_e32 v158, 16, v81
	v_and_b32_e32 v81, 0xffff0000, v81
	v_add_f32_e32 v12, v12, v158
	v_add_f32_e32 v13, v13, v81
	v_lshlrev_b32_e32 v158, 16, v82
	v_and_b32_e32 v82, 0xffff0000, v82
	v_add_f32_e32 v10, v10, v158
	v_add_f32_e32 v11, v11, v82
	v_lshlrev_b32_e32 v158, 16, v83
	v_and_b32_e32 v83, 0xffff0000, v83
	v_add_f32_e32 v8, v8, v158
	v_add_f32_e32 v9, v9, v83
	s_waitcnt vmcnt(17)
	v_lshlrev_b32_e32 v158, 16, v84
	v_and_b32_e32 v84, 0xffff0000, v84
	v_add_f32_e32 v14, v14, v158
	v_add_f32_e32 v15, v15, v84
	v_lshlrev_b32_e32 v158, 16, v85
	v_and_b32_e32 v85, 0xffff0000, v85
	v_add_f32_e32 v12, v12, v158
	v_add_f32_e32 v13, v13, v85
	v_lshlrev_b32_e32 v158, 16, v86
	v_and_b32_e32 v86, 0xffff0000, v86
	v_add_f32_e32 v10, v10, v158
	v_add_f32_e32 v11, v11, v86
	v_lshlrev_b32_e32 v158, 16, v87
	v_and_b32_e32 v87, 0xffff0000, v87
	v_add_f32_e32 v8, v8, v158
	v_add_f32_e32 v9, v9, v87
	s_waitcnt vmcnt(16)
	v_lshlrev_b32_e32 v158, 16, v88
	v_and_b32_e32 v88, 0xffff0000, v88
	v_add_f32_e32 v14, v14, v158
	v_add_f32_e32 v15, v15, v88
	v_lshlrev_b32_e32 v158, 16, v89
	v_and_b32_e32 v89, 0xffff0000, v89
	v_add_f32_e32 v12, v12, v158
	v_add_f32_e32 v13, v13, v89
	v_lshlrev_b32_e32 v158, 16, v90
	v_and_b32_e32 v90, 0xffff0000, v90
	v_add_f32_e32 v10, v10, v158
	v_add_f32_e32 v11, v11, v90
	v_lshlrev_b32_e32 v158, 16, v91
	v_and_b32_e32 v91, 0xffff0000, v91
	v_add_f32_e32 v8, v8, v158
	v_add_f32_e32 v9, v9, v91
	s_waitcnt vmcnt(15)
	v_lshlrev_b32_e32 v158, 16, v92
	v_and_b32_e32 v92, 0xffff0000, v92
	v_add_f32_e32 v14, v14, v158
	v_add_f32_e32 v15, v15, v92
	v_lshlrev_b32_e32 v158, 16, v93
	v_and_b32_e32 v93, 0xffff0000, v93
	v_add_f32_e32 v12, v12, v158
	v_add_f32_e32 v13, v13, v93
	v_lshlrev_b32_e32 v158, 16, v94
	v_and_b32_e32 v94, 0xffff0000, v94
	v_add_f32_e32 v10, v10, v158
	v_add_f32_e32 v11, v11, v94
	v_lshlrev_b32_e32 v158, 16, v95
	v_and_b32_e32 v95, 0xffff0000, v95
	v_add_f32_e32 v8, v8, v158
	v_add_f32_e32 v9, v9, v95
	s_waitcnt vmcnt(14)
	v_lshlrev_b32_e32 v158, 16, v96
	v_and_b32_e32 v96, 0xffff0000, v96
	v_add_f32_e32 v14, v14, v158
	v_add_f32_e32 v15, v15, v96
	v_lshlrev_b32_e32 v158, 16, v97
	v_and_b32_e32 v97, 0xffff0000, v97
	v_add_f32_e32 v12, v12, v158
	v_add_f32_e32 v13, v13, v97
	v_lshlrev_b32_e32 v158, 16, v98
	v_and_b32_e32 v98, 0xffff0000, v98
	v_add_f32_e32 v10, v10, v158
	v_add_f32_e32 v11, v11, v98
	v_lshlrev_b32_e32 v158, 16, v99
	v_and_b32_e32 v99, 0xffff0000, v99
	v_add_f32_e32 v8, v8, v158
	v_add_f32_e32 v9, v9, v99
	s_waitcnt vmcnt(13)
	v_lshlrev_b32_e32 v158, 16, v100
	v_and_b32_e32 v100, 0xffff0000, v100
	v_add_f32_e32 v14, v14, v158
	v_add_f32_e32 v15, v15, v100
	v_lshlrev_b32_e32 v158, 16, v101
	v_and_b32_e32 v101, 0xffff0000, v101
	v_add_f32_e32 v12, v12, v158
	v_add_f32_e32 v13, v13, v101
	v_lshlrev_b32_e32 v158, 16, v102
	v_and_b32_e32 v102, 0xffff0000, v102
	v_add_f32_e32 v10, v10, v158
	v_add_f32_e32 v11, v11, v102
	v_lshlrev_b32_e32 v158, 16, v103
	v_and_b32_e32 v103, 0xffff0000, v103
	v_add_f32_e32 v8, v8, v158
	v_add_f32_e32 v9, v9, v103
	s_waitcnt vmcnt(12)
	v_lshlrev_b32_e32 v158, 16, v104
	v_and_b32_e32 v104, 0xffff0000, v104
	v_add_f32_e32 v14, v14, v158
	v_add_f32_e32 v15, v15, v104
	v_lshlrev_b32_e32 v158, 16, v105
	v_and_b32_e32 v105, 0xffff0000, v105
	v_add_f32_e32 v12, v12, v158
	v_add_f32_e32 v13, v13, v105
	v_lshlrev_b32_e32 v158, 16, v106
	v_and_b32_e32 v106, 0xffff0000, v106
	v_add_f32_e32 v10, v10, v158
	v_add_f32_e32 v11, v11, v106
	v_lshlrev_b32_e32 v158, 16, v107
	v_and_b32_e32 v107, 0xffff0000, v107
	v_add_f32_e32 v8, v8, v158
	v_add_f32_e32 v9, v9, v107
	s_waitcnt vmcnt(11)
	v_lshlrev_b32_e32 v158, 16, v108
	v_and_b32_e32 v108, 0xffff0000, v108
	v_add_f32_e32 v14, v14, v158
	v_add_f32_e32 v15, v15, v108
	v_lshlrev_b32_e32 v158, 16, v109
	v_and_b32_e32 v109, 0xffff0000, v109
	v_add_f32_e32 v12, v12, v158
	v_add_f32_e32 v13, v13, v109
	v_lshlrev_b32_e32 v158, 16, v110
	v_and_b32_e32 v110, 0xffff0000, v110
	v_add_f32_e32 v10, v10, v158
	v_add_f32_e32 v11, v11, v110
	v_lshlrev_b32_e32 v158, 16, v111
	v_and_b32_e32 v111, 0xffff0000, v111
	v_add_f32_e32 v8, v8, v158
	v_add_f32_e32 v9, v9, v111
	s_waitcnt vmcnt(10)
	v_lshlrev_b32_e32 v158, 16, v112
	v_and_b32_e32 v112, 0xffff0000, v112
	v_add_f32_e32 v14, v14, v158
	v_add_f32_e32 v15, v15, v112
	v_lshlrev_b32_e32 v158, 16, v113
	v_and_b32_e32 v113, 0xffff0000, v113
	v_add_f32_e32 v12, v12, v158
	v_add_f32_e32 v13, v13, v113
	v_lshlrev_b32_e32 v158, 16, v114
	v_and_b32_e32 v114, 0xffff0000, v114
	v_add_f32_e32 v10, v10, v158
	v_add_f32_e32 v11, v11, v114
	v_lshlrev_b32_e32 v158, 16, v115
	v_and_b32_e32 v115, 0xffff0000, v115
	v_add_f32_e32 v8, v8, v158
	v_add_f32_e32 v9, v9, v115
	s_waitcnt vmcnt(9)
	v_lshlrev_b32_e32 v158, 16, v116
	v_and_b32_e32 v116, 0xffff0000, v116
	v_add_f32_e32 v14, v14, v158
	v_add_f32_e32 v15, v15, v116
	v_lshlrev_b32_e32 v158, 16, v117
	v_and_b32_e32 v117, 0xffff0000, v117
	v_add_f32_e32 v12, v12, v158
	v_add_f32_e32 v13, v13, v117
	v_lshlrev_b32_e32 v158, 16, v118
	v_and_b32_e32 v118, 0xffff0000, v118
	v_add_f32_e32 v10, v10, v158
	v_add_f32_e32 v11, v11, v118
	v_lshlrev_b32_e32 v158, 16, v119
	v_and_b32_e32 v119, 0xffff0000, v119
	v_add_f32_e32 v8, v8, v158
	v_add_f32_e32 v9, v9, v119
	s_waitcnt vmcnt(8)
	v_lshlrev_b32_e32 v158, 16, v120
	v_and_b32_e32 v120, 0xffff0000, v120
	v_add_f32_e32 v14, v14, v158
	v_add_f32_e32 v15, v15, v120
	v_lshlrev_b32_e32 v158, 16, v121
	v_and_b32_e32 v121, 0xffff0000, v121
	v_add_f32_e32 v12, v12, v158
	v_add_f32_e32 v13, v13, v121
	v_lshlrev_b32_e32 v158, 16, v122
	v_and_b32_e32 v122, 0xffff0000, v122
	v_add_f32_e32 v10, v10, v158
	v_add_f32_e32 v11, v11, v122
	v_lshlrev_b32_e32 v158, 16, v123
	v_and_b32_e32 v123, 0xffff0000, v123
	v_add_f32_e32 v8, v8, v158
	v_add_f32_e32 v9, v9, v123
	s_waitcnt vmcnt(7)
	v_lshlrev_b32_e32 v158, 16, v124
	v_and_b32_e32 v124, 0xffff0000, v124
	v_add_f32_e32 v14, v14, v158
	v_add_f32_e32 v15, v15, v124
	v_lshlrev_b32_e32 v158, 16, v125
	v_and_b32_e32 v125, 0xffff0000, v125
	v_add_f32_e32 v12, v12, v158
	v_add_f32_e32 v13, v13, v125
	v_lshlrev_b32_e32 v158, 16, v126
	v_and_b32_e32 v126, 0xffff0000, v126
	v_add_f32_e32 v10, v10, v158
	v_add_f32_e32 v11, v11, v126
	v_lshlrev_b32_e32 v158, 16, v127
	v_and_b32_e32 v127, 0xffff0000, v127
	v_add_f32_e32 v8, v8, v158
	v_add_f32_e32 v9, v9, v127
	s_waitcnt vmcnt(6)
	v_lshlrev_b32_e32 v158, 16, v128
	v_and_b32_e32 v128, 0xffff0000, v128
	v_add_f32_e32 v14, v14, v158
	v_add_f32_e32 v15, v15, v128
	v_lshlrev_b32_e32 v158, 16, v129
	v_and_b32_e32 v129, 0xffff0000, v129
	v_add_f32_e32 v12, v12, v158
	v_add_f32_e32 v13, v13, v129
	v_lshlrev_b32_e32 v158, 16, v130
	v_and_b32_e32 v130, 0xffff0000, v130
	v_add_f32_e32 v10, v10, v158
	v_add_f32_e32 v11, v11, v130
	v_lshlrev_b32_e32 v158, 16, v131
	v_and_b32_e32 v131, 0xffff0000, v131
	v_add_f32_e32 v8, v8, v158
	v_add_f32_e32 v9, v9, v131
	s_waitcnt vmcnt(5)
	v_lshlrev_b32_e32 v158, 16, v132
	v_and_b32_e32 v132, 0xffff0000, v132
	v_add_f32_e32 v14, v14, v158
	v_add_f32_e32 v15, v15, v132
	v_lshlrev_b32_e32 v158, 16, v133
	v_and_b32_e32 v133, 0xffff0000, v133
	v_add_f32_e32 v12, v12, v158
	v_add_f32_e32 v13, v13, v133
	v_lshlrev_b32_e32 v158, 16, v134
	v_and_b32_e32 v134, 0xffff0000, v134
	v_add_f32_e32 v10, v10, v158
	v_add_f32_e32 v11, v11, v134
	v_lshlrev_b32_e32 v158, 16, v135
	v_and_b32_e32 v135, 0xffff0000, v135
	v_add_f32_e32 v8, v8, v158
	v_add_f32_e32 v9, v9, v135
	s_waitcnt vmcnt(4)
	v_lshlrev_b32_e32 v158, 16, v136
	v_and_b32_e32 v136, 0xffff0000, v136
	v_add_f32_e32 v14, v14, v158
	v_add_f32_e32 v15, v15, v136
	v_lshlrev_b32_e32 v158, 16, v137
	v_and_b32_e32 v137, 0xffff0000, v137
	v_add_f32_e32 v12, v12, v158
	v_add_f32_e32 v13, v13, v137
	v_lshlrev_b32_e32 v158, 16, v138
	v_and_b32_e32 v138, 0xffff0000, v138
	v_add_f32_e32 v10, v10, v158
	v_add_f32_e32 v11, v11, v138
	v_lshlrev_b32_e32 v158, 16, v139
	v_and_b32_e32 v139, 0xffff0000, v139
	v_add_f32_e32 v8, v8, v158
	v_add_f32_e32 v9, v9, v139
	s_waitcnt vmcnt(3)
	v_lshlrev_b32_e32 v158, 16, v140
	v_and_b32_e32 v140, 0xffff0000, v140
	v_add_f32_e32 v14, v14, v158
	v_add_f32_e32 v15, v15, v140
	v_lshlrev_b32_e32 v158, 16, v141
	v_and_b32_e32 v141, 0xffff0000, v141
	v_add_f32_e32 v12, v12, v158
	v_add_f32_e32 v13, v13, v141
	v_lshlrev_b32_e32 v158, 16, v142
	v_and_b32_e32 v142, 0xffff0000, v142
	v_add_f32_e32 v10, v10, v158
	v_add_f32_e32 v11, v11, v142
	v_lshlrev_b32_e32 v158, 16, v143
	v_and_b32_e32 v143, 0xffff0000, v143
	v_add_f32_e32 v8, v8, v158
	v_add_f32_e32 v9, v9, v143
	s_waitcnt vmcnt(2)
	v_lshlrev_b32_e32 v158, 16, v144
	v_and_b32_e32 v144, 0xffff0000, v144
	v_add_f32_e32 v14, v14, v158
	v_add_f32_e32 v15, v15, v144
	v_lshlrev_b32_e32 v158, 16, v145
	v_and_b32_e32 v145, 0xffff0000, v145
	v_add_f32_e32 v12, v12, v158
	v_add_f32_e32 v13, v13, v145
	v_lshlrev_b32_e32 v158, 16, v146
	v_and_b32_e32 v146, 0xffff0000, v146
	v_add_f32_e32 v10, v10, v158
	v_add_f32_e32 v11, v11, v146
	v_lshlrev_b32_e32 v158, 16, v147
	v_and_b32_e32 v147, 0xffff0000, v147
	v_add_f32_e32 v8, v8, v158
	v_add_f32_e32 v9, v9, v147
	s_waitcnt vmcnt(1)
	v_lshlrev_b32_e32 v158, 16, v148
	v_and_b32_e32 v148, 0xffff0000, v148
	v_add_f32_e32 v14, v14, v158
	v_add_f32_e32 v15, v15, v148
	v_lshlrev_b32_e32 v158, 16, v149
	v_and_b32_e32 v149, 0xffff0000, v149
	v_add_f32_e32 v12, v12, v158
	v_add_f32_e32 v13, v13, v149
	v_lshlrev_b32_e32 v158, 16, v150
	v_and_b32_e32 v150, 0xffff0000, v150
	v_add_f32_e32 v10, v10, v158
	v_add_f32_e32 v11, v11, v150
	v_lshlrev_b32_e32 v158, 16, v151
	v_and_b32_e32 v151, 0xffff0000, v151
	v_add_f32_e32 v8, v8, v158
	v_add_f32_e32 v9, v9, v151
	s_waitcnt vmcnt(0)
	v_lshlrev_b32_e32 v158, 16, v152
	v_and_b32_e32 v152, 0xffff0000, v152
	v_add_f32_e32 v14, v14, v158
	v_add_f32_e32 v15, v15, v152
	v_lshlrev_b32_e32 v158, 16, v153
	v_and_b32_e32 v153, 0xffff0000, v153
	v_add_f32_e32 v12, v12, v158
	v_add_f32_e32 v13, v13, v153
	v_lshlrev_b32_e32 v158, 16, v154
	v_and_b32_e32 v154, 0xffff0000, v154
	v_add_f32_e32 v10, v10, v158
	v_add_f32_e32 v11, v11, v154
	v_lshlrev_b32_e32 v158, 16, v155
	v_and_b32_e32 v155, 0xffff0000, v155
	v_add_f32_e32 v8, v8, v158
	v_add_f32_e32 v9, v9, v155
	s_or_b64 exec, exec, s[18:19]
	ds_bpermute_b32 v16, v24, v14
	ds_bpermute_b32 v17, v24, v15
	ds_bpermute_b32 v18, v24, v12
	ds_bpermute_b32 v19, v24, v13
	ds_bpermute_b32 v22, v24, v10
	ds_bpermute_b32 v23, v24, v11
	s_waitcnt lgkmcnt(4)
	v_pk_add_f32 v[14:15], v[14:15], v[16:17]
	ds_bpermute_b32 v16, v25, v14
	s_waitcnt lgkmcnt(3)
	v_pk_add_f32 v[18:19], v[12:13], v[18:19]
	ds_bpermute_b32 v17, v25, v15
	ds_bpermute_b32 v20, v25, v18
	ds_bpermute_b32 v21, v25, v19
	s_waitcnt lgkmcnt(4)
	v_pk_add_f32 v[10:11], v[10:11], v[22:23]
	ds_bpermute_b32 v22, v25, v10
	s_waitcnt lgkmcnt(3)
	v_pk_add_f32 v[12:13], v[14:15], v[16:17]
	ds_bpermute_b32 v23, v25, v11
	s_waitcnt lgkmcnt(2)
	v_pk_add_f32 v[16:17], v[18:19], v[20:21]
	ds_bpermute_b32 v20, v24, v8
	ds_bpermute_b32 v21, v24, v9
	ds_bpermute_b32 v14, v26, v12
	ds_bpermute_b32 v15, v26, v13
	ds_bpermute_b32 v18, v26, v16
	ds_bpermute_b32 v19, v26, v17
	s_waitcnt lgkmcnt(4)
	v_pk_add_f32 v[20:21], v[8:9], v[20:21]
	ds_bpermute_b32 v28, v25, v20
	ds_bpermute_b32 v29, v25, v21
	v_pk_add_f32 v[8:9], v[10:11], v[22:23]
	ds_bpermute_b32 v10, v26, v8
	ds_bpermute_b32 v11, v26, v9
	s_waitcnt lgkmcnt(2)
	v_pk_add_f32 v[20:21], v[20:21], v[28:29]
	ds_bpermute_b32 v22, v26, v20
	ds_bpermute_b32 v23, v26, v21
	s_and_saveexec_b64 s[4:5], s[2:3]
	s_cbranch_execz .LBB0_1219
	v_mov_b64_e32 v[28:29], s[8:9]
	v_mad_i64_i32 v[28:29], s[18:19], v4, s0, v[28:29]
	v_lshl_add_u64 v[6:7], v[6:7], 2, v[28:29]
	v_lshl_add_u64 v[28:29], v[6:7], 0, v[0:1]
	v_pk_add_f32 v[6:7], v[12:13], v[14:15]
	s_nop 0
	v_pk_mul_f32 v[12:13], v[6:7], s[14:15] op_sel_hi:[1,0]
	v_pk_add_f32 v[6:7], v[16:17], v[18:19]
	s_nop 0
	v_pk_mul_f32 v[14:15], v[6:7], s[14:15] op_sel_hi:[1,0]
	s_waitcnt lgkmcnt(2)
	v_pk_add_f32 v[6:7], v[8:9], v[10:11]
	s_waitcnt lgkmcnt(0)
	v_pk_add_f32 v[8:9], v[20:21], v[22:23]
	v_pk_mul_f32 v[6:7], v[6:7], s[14:15] op_sel_hi:[1,0]
	v_pk_mul_f32 v[8:9], v[8:9], s[14:15] op_sel_hi:[1,0]
	global_store_dwordx4 v[28:29], v[12:15], off
	global_store_dwordx4 v[28:29], v[6:9], off offset:16
	s_branch .LBB0_1219
